# MLA tile loop back-edge rotation: next-tile global loads and the scalar loop test issued in front of the barrier
# speedup vs baseline: 1.0048x; 1.0048x over previous
; #define LAS __attribute__((address_space(3)))
; #define LDS_BARRIER() do { asm volatile("s_waitcnt lgkmcnt(0)" ::: "memory"); __builtin_amdgcn_s_barrier(); asm volatile("" ::: "memory"); } while (0)
; template <bool DRY> __device__ __forceinline__ void mla_unit(LAS unsigned char* lds, int b, int h, int qb, const bf16_t* Q, const bf16_t* Kn, const bf16_t* Pm, const bf16_t* VT, bf16_t* Y) {
;     ...
;     for (int t = 0; t < NT; ++t) {
;         LAS unsigned char* kbuf = lds + (t & 1) * MLA_KB; LAS unsigned char* vbuf = lds + 2 * MLA_KB + (t & 1) * MLA_VB;
;         *(LAS u32x4*)(kbuf + ka_dst) = ra; if (tid < 256) *(LAS u32x4*)(kbuf + kb_dst) = rb; *(LAS u32x4*)(vbuf + va_dst) = rv;
;         LDS_BARRIER();
;         if (t + 1 < NT) { ra = *(const u32x4*)(ka_src + (size_t)(t + 1) * 64 * 512); rb = *(const u32x4*)(kb_src + (size_t)(t + 1) * 64 * PW); rv = *(const u32x4*)(va_src + (t + 1) * 64); }
;         if (t <= tmax) {
;             f32x16 p0 = {}, p1 = {};
; #pragma unroll
;             for (int s = 0; s < 6; ++s) {
;                 const bf16x8 a0 = *(const LAS bf16x8*)(kbuf + r32 * MLA_KSTR + s * 32 + hi * 16);
;                 const bf16x8 a1 = *(const LAS bf16x8*)(kbuf + (32 + r32) * MLA_KSTR + s * 32 + hi * 16);
;                 p0 = __builtin_amdgcn_mfma_f32_32x32x16_bf16(a0, qf[s], p0, 0, 0, 0);
;                 p1 = __builtin_amdgcn_mfma_f32_32x32x16_bf16(a1, qf[s], p1, 0, 0, 0);
;             }
;             float mx = fmaxf(p0[0], p1[0]);
; #pragma unroll
;             for (int r = 1; r < 16; ++r) mx = fmaxf(mx, fmaxf(p0[r], p1[r]));
;             mx = fmaxf(mx, __shfl_xor(mx, 32));
;             const float cand = mx * C; const bool grow = cand > m_run + 8.f;
;             const float m_new = grow ? cand : m_run; const bool anyg = __any(grow);
;             const float alpha = anyg ? __builtin_amdgcn_exp2f(m_run - m_new) : 1.f; m_run = m_new;
;             float ls = 0.f;
; #pragma unroll
;             for (int r = 0; r < 16; ++r) { p0[r] = __builtin_amdgcn_exp2f(p0[r] * C - m_new); p1[r] = __builtin_amdgcn_exp2f(p1[r] * C - m_new); ls += p0[r] + p1[r]; }
;             if (anyg) { l_run *= alpha;
; #pragma unroll
;                 for (int r = 0; r < 16; ++r) { o0[r] *= alpha; o1[r] *= alpha; } }
.LBB0_802:
	s_and_b32 s59, s57, 1
	s_mul_i32 s22, s59, 0x3400
	s_add_i32 s58, s22, 0
	s_lshl_b32 s22, s59, 12
	s_sub_i32 s23, s58, s22
	s_waitcnt lgkmcnt(0)
	s_add_i32 s22, s57, 1
	s_cmp_ge_u32 s22, s41
	s_cbranch_scc1 .Lmla_nl
	v_lshl_add_u64 v[0:1], s[28:29], 1, v[114:115]
	global_load_dwordx4 v[100:103], v[118:119], off
	global_load_dwordx4 v[96:99], v[116:117], off
	global_load_dwordx4 v[88:91], v[0:1], off
.Lmla_nl:
	s_barrier
.LBB0_806:
	s_cmp_gt_i32 s57, s56
	s_cbranch_scc1 .LBB0_810
	v_add3_u32 v0, s58, v113, v108
	ds_read_b128 v[36:39], v0
	ds_read_b128 v[132:135], v0 offset:32
	ds_read_b128 v[52:55], v0 offset:6656
	ds_read_b128 v[136:139], v0 offset:6688
	ds_read_b128 v[140:143], v0 offset:64
	ds_read_b128 v[144:147], v0 offset:6720
	ds_read_b128 v[148:151], v0 offset:96
	ds_read_b128 v[152:155], v0 offset:6752
	ds_read_b128 v[156:159], v0 offset:128
	ds_read_b128 v[160:163], v0 offset:6784
	ds_read_b128 v[164:167], v0 offset:6816
	ds_read_b128 v[168:171], v0 offset:160
	s_waitcnt lgkmcnt(11)
	v_mfma_f32_32x32x16_bf16 v[36:51], v[36:39], v[84:87], 0
	s_waitcnt lgkmcnt(10)
	v_mfma_f32_32x32x16_bf16 v[36:51], v[132:135], v[68:71], v[36:51]
	s_waitcnt lgkmcnt(9)
	v_mfma_f32_32x32x16_bf16 v[52:67], v[52:55], v[84:87], 0
	s_waitcnt lgkmcnt(8)
	v_mfma_f32_32x32x16_bf16 v[52:67], v[136:139], v[68:71], v[52:67]
	s_waitcnt lgkmcnt(7)
	v_mfma_f32_32x32x16_bf16 v[36:51], v[140:143], v[72:75], v[36:51]
	s_waitcnt lgkmcnt(6)
	v_mfma_f32_32x32x16_bf16 v[52:67], v[144:147], v[72:75], v[52:67]
	s_waitcnt lgkmcnt(5)
	v_mfma_f32_32x32x16_bf16 v[36:51], v[148:151], v[76:79], v[36:51]
	s_waitcnt lgkmcnt(4)
	v_mfma_f32_32x32x16_bf16 v[52:67], v[152:155], v[76:79], v[52:67]
	s_waitcnt lgkmcnt(3)
	v_mfma_f32_32x32x16_bf16 v[36:51], v[156:159], v[80:83], v[36:51]
	s_waitcnt lgkmcnt(2)
	v_mfma_f32_32x32x16_bf16 v[52:67], v[160:163], v[80:83], v[52:67]
	s_waitcnt lgkmcnt(1)
	v_mfma_f32_32x32x16_bf16 v[52:67], v[164:167], v[92:95], v[52:67]
	s_waitcnt lgkmcnt(0)
	v_mfma_f32_32x32x16_bf16 v[36:51], v[168:171], v[92:95], v[36:51]
	v_add3_u32 v130, s23, v120, v106
	v_add_u32_e32 v129, 0x7800, v130
	v_add_u32_e32 v130, 0x6800, v130
	ds_read2_b64 v[172:175], v130 offset1:2
	ds_read2_b64 v[176:179], v129 offset0:64 offset1:66
	ds_read2_b64 v[180:183], v130 offset0:4 offset1:6
	ds_read2_b64 v[184:187], v129 offset0:68 offset1:70
	ds_read2_b64 v[188:191], v130 offset0:8 offset1:10
	ds_read2_b64 v[192:195], v129 offset0:72 offset1:74
	ds_read2_b64 v[196:199], v130 offset0:12 offset1:14
	ds_read2_b64 v[212:215], v129 offset0:76 offset1:78
	s_nop 1
	v_max3_f32 v0, v36, v52, v37
	v_max3_f32 v1, v53, v38, v54
	v_max3_f32 v0, v0, v39, v55
	v_max3_f32 v1, v1, v40, v56
	v_max3_f32 v0, v0, v41, v57
	v_max3_f32 v1, v1, v42, v58
	v_max3_f32 v0, v0, v43, v59
	v_max3_f32 v1, v1, v44, v60
	v_max3_f32 v0, v0, v45, v61
	v_max3_f32 v1, v1, v46, v62
	v_max3_f32 v0, v0, v47, v63
	v_max3_f32 v1, v1, v48, v64
	v_max3_f32 v0, v0, v49, v65
	v_max3_f32 v1, v1, v50, v66
	v_max3_f32 v0, v0, v51, v67
	v_max_f32_e32 v0, v0, v1
	v_mov_b32_e32 v1, v0
	v_mov_b32_e32 v3, v0
	s_nop 1
	v_permlane32_swap_b32_e32 v1, v3
	v_max_f32_e32 v0, v1, v3
	v_mul_f32_e32 v0, 0x3e16c740, v0
	v_add_f32_e32 v1, 0x41000000, v122
	v_cmp_gt_f32_e32 vcc, v0, v1
	s_nop 1
	v_cndmask_b32_e32 v0, v122, v0, vcc
	s_cbranch_vccz .LBB0_809
	v_sub_f32_e32 v1, v122, v0
	v_exp_f32_e32 v122, v1
	s_nop 0
	v_pk_mul_f32 v[34:35], v[34:35], v[122:123] op_sel_hi:[1,0]
	v_pk_mul_f32 v[32:33], v[32:33], v[122:123] op_sel_hi:[1,0]
	v_pk_mul_f32 v[30:31], v[30:31], v[122:123] op_sel_hi:[1,0]
	v_pk_mul_f32 v[28:29], v[28:29], v[122:123] op_sel_hi:[1,0]
	v_pk_mul_f32 v[26:27], v[26:27], v[122:123] op_sel_hi:[1,0]
	v_pk_mul_f32 v[24:25], v[24:25], v[122:123] op_sel_hi:[1,0]
	v_pk_mul_f32 v[22:23], v[22:23], v[122:123] op_sel_hi:[1,0]
	v_pk_mul_f32 v[20:21], v[20:21], v[122:123] op_sel_hi:[1,0]
	v_pk_mul_f32 v[18:19], v[18:19], v[122:123] op_sel_hi:[1,0]
	v_pk_mul_f32 v[16:17], v[16:17], v[122:123] op_sel_hi:[1,0]
	v_pk_mul_f32 v[14:15], v[14:15], v[122:123] op_sel_hi:[1,0]
	v_pk_mul_f32 v[12:13], v[12:13], v[122:123] op_sel_hi:[1,0]
	v_pk_mul_f32 v[10:11], v[10:11], v[122:123] op_sel_hi:[1,0]
	v_pk_mul_f32 v[8:9], v[8:9], v[122:123] op_sel_hi:[1,0]
	v_pk_mul_f32 v[6:7], v[6:7], v[122:123] op_sel_hi:[1,0]
	v_pk_mul_f32 v[4:5], v[4:5], v[122:123] op_sel_hi:[1,0]
	v_mul_f32_e32 v121, v121, v122
